# v62 plus w_in GEMM: first K iteration after a tile epilogue peeled, its first two counted waits skip the 16 epilogue stores queued in front of the loads
# speedup vs baseline: 1.0073x; 1.0018x over previous
; #define PG8_STAGE(bufoff, gbase, voff) do { _Pragma("unroll") for (int _i = 0; _i < 2; ++_i) \
;         __builtin_amdgcn_global_load_lds((const unsigned*)((const char*)(gbase) + (voff)[_i]), (PG8_LAS unsigned*)(lds + (bufoff) + ldsw + _i * 8192), 16, 0, 0); } while (0)
; #define PG8_WAIT_V(n) asm volatile("s_waitcnt vmcnt(" #n ")" ::: "memory")
; #define PG8_BAR __builtin_amdgcn_s_barrier()
; template <class Epi, class Sched, bool ALIGN_EPI = false, bool SP2 = false>
; __device__ __forceinline__ void gemm_phase(PG8_LAS unsigned char* lds, const Gemm g, const Sched& S, const Epi& E) {
;     ...
;     const int tid = tid_, wid = __builtin_amdgcn_readfirstlane(tid >> 6), lane = tid & 63, wr = wid >> 2, wc = wid & 3, fr = lane & 15, fq = lane >> 4;
;     const int K = g.K, nt = K / BK;
;     unsigned voffA[2], voffB[2];
; #pragma unroll
;     for (int i = 0; i < 2; ++i) { int R, C; stage_rc(tid * 16 + i * 8192, R, C); const int Rb = Epi::PERM ? ((R & ~31) + perm32(R & 31)) : R;
;         voffA[i] = (unsigned)(R * K + C) * 2u; voffB[i] = (unsigned)(Rb * K + C) * 2u; }
;     const size_t kstep = (size_t)(BK * 2);
;     const size_t hstep = (size_t)HALF * K * 2;
;     const size_t tstep = 2 * hstep;
;     const unsigned ldsw = (unsigned)wid * 1024u;
;     const int aoff = lds_byte(wr * 64 + fr, fq * 8), boff = lds_byte(wc * 32 + fr, fq * 8);
;     ...
;         PG8_STAGE(PG8_SB(0, 0), cB, voffB); PG8_STAGE(PG8_SB(0, 1), cB + hstep, voffB); PG8_STAGE(PG8_SA(0, 0), cA, voffA); PG8_STAGE(PG8_SA(0, 1), cA + hstep, voffA);
;         if (wr == 1) PG8_BAR;
;         PG8_WAIT_V(2); PG8_BAR;
;         PG8_STAGE(PG8_SB(1, 0), cB + kstep, voffB); PG8_STAGE(PG8_SA(1, 0), cA + kstep, voffA); PG8_STAGE(PG8_SB(1, 1), cB + hstep + kstep, voffB);
;         PG8_WAIT_V(6); PG8_BAR;
.LBB0_665:
	s_mov_b32 s32, 0
	s_add_u32 s10, s4, 0x40400000
	s_addc_u32 s11, s5, 0
	s_add_u32 s12, s4, 0x4f400000
	s_addc_u32 s13, s5, 0
	s_add_u32 s28, s4, 0x4d400000
	s_addc_u32 s29, s5, 0
	s_and_b32 s7, s1, 3
	s_add_i32 m0, s39, 0x18000
	v_lshl_add_u64 v[10:11], v[10:11], 0, s[16:17]
	s_lshl_b32 s30, s6, 13
	s_lshl_b32 s31, s7, 12
	s_waitcnt vmcnt(2)
	s_barrier
	global_load_lds_dwordx4 v[10:11], off
	v_lshl_add_u64 v[8:9], v[8:9], 0, s[16:17]
	s_add_i32 m0, s39, 0x1a000
	s_add_i32 s54, s39, 0x8000
	s_add_i32 s55, s39, 0xa000
	global_load_lds_dwordx4 v[8:9], off
	v_lshl_add_u64 v[4:5], v[4:5], 0, s[16:17]
	s_mov_b32 m0, s54
	s_add_u32 s4, s42, 0x80080
	global_load_lds_dwordx4 v[4:5], off
	v_lshl_add_u64 v[4:5], v[6:7], 0, s[16:17]
	s_mov_b32 m0, s55
	s_addc_u32 s5, s43, 0
	global_load_lds_dwordx4 v[4:5], off
	s_add_i32 m0, s39, 0x1c000
	v_lshl_add_u64 v[4:5], s[4:5], 0, v[2:3]
	global_load_lds_dwordx4 v[4:5], off
	v_lshl_add_u64 v[4:5], s[4:5], 0, v[148:149]
	s_add_i32 m0, s39, 0x1e000
	v_bfe_u32 v6, v1, 4, 2
	global_load_lds_dwordx4 v[4:5], off
	v_and_b32_e32 v5, 15, v1
	v_lshlrev_b32_e32 v8, 4, v6
	v_lshrrev_b32_e32 v4, 4, v1
	v_lshl_or_b32 v1, s6, 6, v5
	v_lshl_or_b32 v8, v5, 6, v8
	v_lshlrev_b32_e32 v5, 2, v5
	v_and_b32_e32 v9, 32, v5
	s_cmpk_lt_u32 s0, 0x100
	v_bitop3_b32 v10, v8, s30, v9 bitop3:0xde
	v_bitop3_b32 v173, v8, s31, v9 bitop3:0xde
	s_cselect_b64 s[30:31], -1, 0
	s_lshl_b32 s4, s6, 8
	s_add_i32 s5, 0, 0x20400
	s_add_i32 s4, s5, s4
	v_bitop3_b32 v4, s1, v4, 3 bitop3:0xa8
	v_add_u32_e32 v178, s4, v5
	s_lshl_b32 s4, s7, 7
	v_cmp_eq_u32_e64 s[0:1], 0, v4
	v_lshlrev_b32_e32 v4, 5, v6
	s_add_i32 s5, s4, s5
	s_add_i32 s4, s4, 0
	v_add_u32_e32 v179, s5, v4
	s_add_i32 s5, s4, 0x20410
	v_add_u32_e32 v180, s5, v4
	s_add_i32 s5, s4, 0x20600
	s_add_i32 s4, s4, 0x20610
	v_add_u32_e32 v181, s5, v4
	v_add_u32_e32 v182, s4, v4
	v_lshlrev_b32_e32 v4, 15, v16
	v_and_b32_e32 v4, 0xffff0000, v4
	v_lshl_add_u32 v4, v15, 12, v4
	v_and_b32_e32 v5, 1, v16
	v_lshl_or_b32 v4, v5, 6, v4
	v_lshl_add_u32 v154, v17, 1, v4
	v_lshlrev_b32_e32 v4, 15, v12
	v_and_b32_e32 v4, 0xffff0000, v4
	s_waitcnt vmcnt(6)
	v_lshl_add_u32 v4, v13, 12, v4
	v_and_b32_e32 v5, 1, v12
	v_lshlrev_b32_e32 v7, 3, v6
	v_lshl_or_b32 v4, v5, 6, v4
	s_mov_b32 s56, 0
	s_ashr_i32 s57, s26, 31
	v_lshl_or_b32 v183, s7, 6, v7
	v_lshl_or_b32 v203, s7, 5, v7
	v_mov_b32_e32 v155, v3
	v_lshl_add_u32 v156, v14, 1, v4
	v_mov_b32_e32 v157, v3
	v_add_u32_e32 v204, 0, v10
	s_barrier
	s_waitcnt vmcnt(0)
	s_branch .LBB0_668

; #define PG8_STAGE(bufoff, gbase, voff) do { _Pragma("unroll") for (int _i = 0; _i < 2; ++_i) \
;         __builtin_amdgcn_global_load_lds((const unsigned*)((const char*)(gbase) + (voff)[_i]), (PG8_LAS unsigned*)(lds + (bufoff) + ldsw + _i * 8192), 16, 0, 0); } while (0)
; #define PG8_LDA(dst, b, h) do { _Pragma("unroll") for (int m = 0; m < 4; ++m) _Pragma("unroll") for (int k = 0; k < 2; ++k) dst[m][k] = *(const PG8_LAS bf16x8*)(lds + PG8_SA(b, h) + aoff + m * 2048 + k * 1024); } while (0)
; #define PG8_LDB(dst, b, h) do { _Pragma("unroll") for (int n = 0; n < 2; ++n) _Pragma("unroll") for (int k = 0; k < 2; ++k) dst[n][k] = *(const PG8_LAS bf16x8*)(lds + PG8_SB(b, h) + boff + n * 2048 + k * 1024); } while (0)
; #define PG8_MMA(ai, bj, At, Bt) do { __builtin_amdgcn_s_setprio(1); _Pragma("unroll") for (int m = 0; m < 4; ++m) _Pragma("unroll") for (int n = 0; n < 2; ++n) _Pragma("unroll") for (int k = 0; k < 2; ++k) \
;         acc[ai][bj][m][n] = __builtin_amdgcn_mfma_f32_16x16x32_bf16(Bt[n][k], At[m][k], acc[ai][bj][m][n], 0, 0, 0); __builtin_amdgcn_s_setprio(0); } while (0)
; #define PG8_WAIT_V(n) asm volatile("s_waitcnt vmcnt(" #n ")" ::: "memory")
; #define PG8_WAIT_L(n) asm volatile("s_waitcnt lgkmcnt(" #n ")" ::: "memory")
; #define PG8_BAR __builtin_amdgcn_s_barrier()
; #define PG8_SCHED __builtin_amdgcn_sched_barrier(0)
; template <class Epi, class Sched, bool ALIGN_EPI = false, bool SP2 = false>
; __device__ __forceinline__ void gemm_phase(PG8_LAS unsigned char* lds, const Gemm g, const Sched& S, const Epi& E) {
;     ...
;             PG8_LDB(B0, 0, 0); PG8_LDB(B1, 0, 1); PG8_SCHED; PG8_LDA(At, 0, 0); PG8_STAGE(PG8_SA(1, 1), a1 + hstep, voffA);
;             PG8_WAIT_V(8); PG8_WAIT_L(0); PG8_BAR; PG8_MMA(0, 0, At, B0); PG8_MMA(0, 1, At, B1); PG8_BAR; PG8_SCHED;
;     ...
;         bool zero_acc = true; if constexpr (Epi::KEEP_ACC) zero_acc = (cur.aux == 2);
;         if (zero_acc) {
; #pragma unroll
;         for (int a = 0; a < 2; ++a)
; #pragma unroll
;             for (int b = 0; b < 2; ++b)
; #pragma unroll
;                 for (int m = 0; m < 4; ++m)
; #pragma unroll
;                     for (int n = 0; n < 2; ++n) acc[a][b][m][n] = (f32x4){0.f, 0.f, 0.f, 0.f};
.LBB0_673:
	s_add_u32 s40, s40, 0x80080
	s_addc_u32 s41, s41, 0
	s_add_u32 s35, s42, 0x100
	v_mov_b32_e32 v4, 0
	s_addc_u32 s62, s43, 0
	s_mov_b32 s63, -2
	v_mov_b32_e32 v5, v4
	v_mov_b32_e32 v6, v4
	v_mov_b32_e32 v7, v4
	v_mov_b32_e32 v8, v4
	v_mov_b32_e32 v9, v4
	v_mov_b32_e32 v10, v4
	v_mov_b32_e32 v11, v4
	v_mov_b32_e32 v16, v4
	v_mov_b32_e32 v17, v4
	v_mov_b32_e32 v18, v4
	v_mov_b32_e32 v19, v4
	v_mov_b32_e32 v24, v4
	v_mov_b32_e32 v25, v4
	v_mov_b32_e32 v26, v4
	v_mov_b32_e32 v27, v4
	v_mov_b32_e32 v32, v4
	v_mov_b32_e32 v33, v4
	v_mov_b32_e32 v34, v4
	v_mov_b32_e32 v35, v4
	v_mov_b32_e32 v40, v4
	v_mov_b32_e32 v41, v4
	v_mov_b32_e32 v42, v4
	v_mov_b32_e32 v43, v4
	v_mov_b32_e32 v48, v4
	v_mov_b32_e32 v49, v4
	v_mov_b32_e32 v50, v4
	v_mov_b32_e32 v51, v4
	v_mov_b32_e32 v56, v4
	v_mov_b32_e32 v57, v4
	v_mov_b32_e32 v58, v4
	v_mov_b32_e32 v59, v4
	v_mov_b32_e32 v12, v4
	v_mov_b32_e32 v13, v4
	v_mov_b32_e32 v14, v4
	v_mov_b32_e32 v15, v4
	v_mov_b32_e32 v20, v4
	v_mov_b32_e32 v21, v4
	v_mov_b32_e32 v22, v4
	v_mov_b32_e32 v23, v4
	v_mov_b32_e32 v28, v4
	v_mov_b32_e32 v29, v4
	v_mov_b32_e32 v30, v4
	v_mov_b32_e32 v31, v4
	v_mov_b32_e32 v36, v4
	v_mov_b32_e32 v37, v4
	v_mov_b32_e32 v38, v4
	v_mov_b32_e32 v39, v4
	v_mov_b32_e32 v44, v4
	v_mov_b32_e32 v45, v4
	v_mov_b32_e32 v46, v4
	v_mov_b32_e32 v47, v4
	v_mov_b32_e32 v52, v4
	v_mov_b32_e32 v53, v4
	v_mov_b32_e32 v54, v4
	v_mov_b32_e32 v55, v4
	v_mov_b32_e32 v60, v4
	v_mov_b32_e32 v61, v4
	v_mov_b32_e32 v62, v4
	v_mov_b32_e32 v63, v4
	v_mov_b32_e32 v64, v4
	v_mov_b32_e32 v65, v4
	v_mov_b32_e32 v66, v4
	v_mov_b32_e32 v67, v4
	v_mov_b32_e32 v68, v4
	v_mov_b32_e32 v69, v4
	v_mov_b32_e32 v70, v4
	v_mov_b32_e32 v71, v4
	v_mov_b32_e32 v72, v4
	v_mov_b32_e32 v73, v4
	v_mov_b32_e32 v74, v4
	v_mov_b32_e32 v75, v4
	v_mov_b32_e32 v80, v4
	v_mov_b32_e32 v81, v4
	v_mov_b32_e32 v82, v4
	v_mov_b32_e32 v83, v4
	v_mov_b32_e32 v88, v4
	v_mov_b32_e32 v89, v4
	v_mov_b32_e32 v90, v4
	v_mov_b32_e32 v91, v4
	v_mov_b32_e32 v96, v4
	v_mov_b32_e32 v97, v4
	v_mov_b32_e32 v98, v4
	v_mov_b32_e32 v99, v4
	v_mov_b32_e32 v104, v4
	v_mov_b32_e32 v105, v4
	v_mov_b32_e32 v106, v4
	v_mov_b32_e32 v107, v4
	v_mov_b32_e32 v112, v4
	v_mov_b32_e32 v113, v4
	v_mov_b32_e32 v114, v4
	v_mov_b32_e32 v115, v4
	v_mov_b32_e32 v120, v4
	v_mov_b32_e32 v121, v4
	v_mov_b32_e32 v122, v4
	v_mov_b32_e32 v123, v4
	v_mov_b32_e32 v76, v4
	v_mov_b32_e32 v77, v4
	v_mov_b32_e32 v78, v4
	v_mov_b32_e32 v79, v4
	v_mov_b32_e32 v84, v4
	v_mov_b32_e32 v85, v4
	v_mov_b32_e32 v86, v4
	v_mov_b32_e32 v87, v4
	v_mov_b32_e32 v92, v4
	v_mov_b32_e32 v93, v4
	v_mov_b32_e32 v94, v4
	v_mov_b32_e32 v95, v4
	v_mov_b32_e32 v100, v4
	v_mov_b32_e32 v101, v4
	v_mov_b32_e32 v102, v4
	v_mov_b32_e32 v103, v4
	v_mov_b32_e32 v108, v4
	v_mov_b32_e32 v109, v4
	v_mov_b32_e32 v110, v4
	v_mov_b32_e32 v111, v4
	v_mov_b32_e32 v116, v4
	v_mov_b32_e32 v117, v4
	v_mov_b32_e32 v118, v4
	v_mov_b32_e32 v119, v4
	v_mov_b32_e32 v124, v4
	v_mov_b32_e32 v125, v4
	v_mov_b32_e32 v126, v4
	v_mov_b32_e32 v127, v4
	v_mov_b32_e32 v128, v4
	v_mov_b32_e32 v129, v4
	v_mov_b32_e32 v130, v4
	v_mov_b32_e32 v131, v4
	v_add_u32_e32 v249, 0x10000, v173
	ds_read_b128 v[132:135], v249
	ds_read_b128 v[136:139], v249 offset:1024
	ds_read_b128 v[140:143], v249 offset:2048
	ds_read_b128 v[144:147], v249 offset:3072
	s_cmp_eq_u32 s32, 0
	s_cbranch_scc1 .LBB0_674
	s_add_u32 s42, s40, 0xfff80080
	s_addc_u32 s43, s41, -1
	s_add_i32 s64, 0, 0x10000
	s_cmp_eq_u32 s63, 28
	s_cselect_b32 s45, s5, s43
	s_cselect_b32 s44, s4, s42
	s_cselect_b32 s43, s37, s62
	s_cselect_b32 s42, s36, s35
	s_add_i32 s66, 0, 0x14000
	ds_read_b128 v[158:161], v249 offset:16384
	ds_read_b128 v[174:177], v249 offset:17408
	ds_read_b128 v[206:209], v249 offset:18432
	ds_read_b128 v[210:213], v249 offset:19456
	s_add_i32 m0, s39, 0xc000
	ds_read_b128 v[214:217], v204
	ds_read_b128 v[218:221], v204 offset:1024
	ds_read_b128 v[222:225], v204 offset:2048
	ds_read_b128 v[226:229], v204 offset:3072
	ds_read_b128 v[230:233], v204 offset:4096
	ds_read_b128 v[234:237], v204 offset:5120
	ds_read_b128 v[238:241], v204 offset:6144
	ds_read_b128 v[242:245], v204 offset:7168
	global_load_lds_dwordx4 v154, s[40:41]
	s_add_i32 m0, s39, 0xe000
	s_nop 0
	global_load_lds_dwordx4 v156, s[40:41]
	s_waitcnt vmcnt(24) lgkmcnt(0)
	s_setprio 0
	s_barrier
	v_mfma_f32_16x16x32_bf16 v[128:131], v[132:135], v[214:217], v[128:131]
	v_mfma_f32_16x16x32_bf16 v[124:127], v[140:143], v[214:217], v[124:127]
	v_mfma_f32_16x16x32_bf16 v[116:119], v[132:135], v[222:225], v[116:119]
	v_mfma_f32_16x16x32_bf16 v[108:111], v[140:143], v[222:225], v[108:111]
	v_mfma_f32_16x16x32_bf16 v[100:103], v[132:135], v[230:233], v[100:103]
	v_mfma_f32_16x16x32_bf16 v[92:95], v[140:143], v[230:233], v[92:95]
	v_mfma_f32_16x16x32_bf16 v[84:87], v[132:135], v[238:241], v[84:87]
	v_mfma_f32_16x16x32_bf16 v[76:79], v[140:143], v[238:241], v[76:79]
	v_mfma_f32_16x16x32_bf16 v[128:131], v[136:139], v[218:221], v[128:131]
	v_mfma_f32_16x16x32_bf16 v[124:127], v[144:147], v[218:221], v[124:127]
	v_mfma_f32_16x16x32_bf16 v[116:119], v[136:139], v[226:229], v[116:119]
	v_mfma_f32_16x16x32_bf16 v[108:111], v[144:147], v[226:229], v[108:111]
	v_mfma_f32_16x16x32_bf16 v[100:103], v[136:139], v[234:237], v[100:103]
	v_mfma_f32_16x16x32_bf16 v[92:95], v[144:147], v[234:237], v[92:95]
	v_mfma_f32_16x16x32_bf16 v[84:87], v[136:139], v[242:245], v[84:87]
	v_mfma_f32_16x16x32_bf16 v[76:79], v[144:147], v[242:245], v[76:79]
	v_mfma_f32_16x16x32_bf16 v[120:123], v[158:161], v[214:217], v[120:123]
	v_mfma_f32_16x16x32_bf16 v[112:115], v[206:209], v[214:217], v[112:115]
	v_mfma_f32_16x16x32_bf16 v[104:107], v[158:161], v[222:225], v[104:107]
	v_mfma_f32_16x16x32_bf16 v[96:99], v[206:209], v[222:225], v[96:99]
	v_mfma_f32_16x16x32_bf16 v[88:91], v[158:161], v[230:233], v[88:91]
	v_mfma_f32_16x16x32_bf16 v[80:83], v[206:209], v[230:233], v[80:83]
	v_mfma_f32_16x16x32_bf16 v[72:75], v[158:161], v[238:241], v[72:75]
	v_mfma_f32_16x16x32_bf16 v[68:71], v[206:209], v[238:241], v[68:71]
	v_mfma_f32_16x16x32_bf16 v[120:123], v[174:177], v[218:221], v[120:123]
	v_mfma_f32_16x16x32_bf16 v[112:115], v[210:213], v[218:221], v[112:115]
	v_mfma_f32_16x16x32_bf16 v[104:107], v[174:177], v[226:229], v[104:107]
	v_mfma_f32_16x16x32_bf16 v[96:99], v[210:213], v[226:229], v[96:99]
	v_mfma_f32_16x16x32_bf16 v[88:91], v[174:177], v[234:237], v[88:91]
	v_mfma_f32_16x16x32_bf16 v[80:83], v[210:213], v[234:237], v[80:83]
	v_mfma_f32_16x16x32_bf16 v[72:75], v[174:177], v[242:245], v[72:75]
	v_mfma_f32_16x16x32_bf16 v[68:71], v[210:213], v[242:245], v[68:71]
	s_setprio 3
	s_barrier
; #define PG8_STAGE(bufoff, gbase, voff) do { _Pragma("unroll") for (int _i = 0; _i < 2; ++_i) \
;         __builtin_amdgcn_global_load_lds((const unsigned*)((const char*)(gbase) + (voff)[_i]), (PG8_LAS unsigned*)(lds + (bufoff) + ldsw + _i * 8192), 16, 0, 0); } while (0)
; #define PG8_LDA(dst, b, h) do { _Pragma("unroll") for (int m = 0; m < 4; ++m) _Pragma("unroll") for (int k = 0; k < 2; ++k) dst[m][k] = *(const PG8_LAS bf16x8*)(lds + PG8_SA(b, h) + aoff + m * 2048 + k * 1024); } while (0)
; #define PG8_LDB(dst, b, h) do { _Pragma("unroll") for (int n = 0; n < 2; ++n) _Pragma("unroll") for (int k = 0; k < 2; ++k) dst[n][k] = *(const PG8_LAS bf16x8*)(lds + PG8_SB(b, h) + boff + n * 2048 + k * 1024); } while (0)
; #define PG8_MMA(ai, bj, At, Bt) do { __builtin_amdgcn_s_setprio(1); _Pragma("unroll") for (int m = 0; m < 4; ++m) _Pragma("unroll") for (int n = 0; n < 2; ++n) _Pragma("unroll") for (int k = 0; k < 2; ++k) \
;         acc[ai][bj][m][n] = __builtin_amdgcn_mfma_f32_16x16x32_bf16(Bt[n][k], At[m][k], acc[ai][bj][m][n], 0, 0, 0); __builtin_amdgcn_s_setprio(0); } while (0)
; #define PG8_WAIT_V(n) asm volatile("s_waitcnt vmcnt(" #n ")" ::: "memory")
; #define PG8_WAIT_L(n) asm volatile("s_waitcnt lgkmcnt(" #n ")" ::: "memory")
; #define PG8_BAR __builtin_amdgcn_s_barrier()
; #define PG8_SCHED __builtin_amdgcn_sched_barrier(0)
; template <class Epi, class Sched, bool ALIGN_EPI = false, bool SP2 = false>
; __device__ __forceinline__ void gemm_phase(PG8_LAS unsigned char* lds, const Gemm g, const Sched& S, const Epi& E) {
;     ...
;             PG8_LDA(At, 0, 1); PG8_STAGE(PG8_SB(0, 0), b2, voffB); PG8_STAGE(PG8_SB(0, 1), b2 + hstep, voffB); PG8_STAGE(PG8_SA(0, 0), a2, voffA);
;             PG8_WAIT_V(8); PG8_WAIT_L(0); PG8_BAR; PG8_MMA(1, 0, At, B0); PG8_MMA(1, 1, At, B1); PG8_BAR; PG8_SCHED;
;             PG8_LDB(B0, 1, 0); PG8_LDB(B1, 1, 1); PG8_SCHED; PG8_LDA(At, 1, 0); PG8_STAGE(PG8_SA(0, 1), a2 + hstep, voffA);
;             PG8_WAIT_V(8); PG8_WAIT_L(0); PG8_BAR; PG8_MMA(0, 0, At, B0); PG8_MMA(0, 1, At, B1); PG8_BAR; PG8_SCHED;
	s_add_i32 s64, s64, s46
	s_mov_b32 m0, s64
	ds_read_b128 v[214:217], v204 offset:16384
	ds_read_b128 v[218:221], v204 offset:17408
	ds_read_b128 v[222:225], v204 offset:18432
	ds_read_b128 v[226:229], v204 offset:19456
	ds_read_b128 v[230:233], v204 offset:20480
	ds_read_b128 v[234:237], v204 offset:21504
	ds_read_b128 v[238:241], v204 offset:22528
	ds_read_b128 v[242:245], v204 offset:23552
	global_load_lds_dwordx4 v2, s[42:43]
	s_add_i32 m0, s64, 0x2000
	s_add_u32 s64, s42, 0x80000
	s_addc_u32 s65, s43, 0
	s_add_i32 s66, s66, s46
	global_load_lds_dwordx4 v148, s[42:43]
	s_mov_b32 m0, s66
	s_nop 0
	global_load_lds_dwordx4 v2, s[64:65]
	s_add_i32 m0, s66, 0x2000
	s_nop 0
	global_load_lds_dwordx4 v148, s[64:65]
	s_mov_b32 m0, s39
	s_nop 0
	global_load_lds_dwordx4 v152, s[44:45]
	s_mov_b32 m0, s51
	s_nop 0
	global_load_lds_dwordx4 v150, s[44:45]
	s_waitcnt vmcnt(24) lgkmcnt(0)
	s_setprio 0
	s_barrier
	v_mfma_f32_16x16x32_bf16 v[64:67], v[132:135], v[214:217], v[64:67]
	v_mfma_f32_16x16x32_bf16 v[60:63], v[140:143], v[214:217], v[60:63]
	v_mfma_f32_16x16x32_bf16 v[52:55], v[132:135], v[222:225], v[52:55]
	v_mfma_f32_16x16x32_bf16 v[44:47], v[140:143], v[222:225], v[44:47]
	v_mfma_f32_16x16x32_bf16 v[36:39], v[132:135], v[230:233], v[36:39]
	v_mfma_f32_16x16x32_bf16 v[28:31], v[140:143], v[230:233], v[28:31]
	v_mfma_f32_16x16x32_bf16 v[20:23], v[132:135], v[238:241], v[20:23]
	v_mfma_f32_16x16x32_bf16 v[12:15], v[140:143], v[238:241], v[12:15]
	v_mfma_f32_16x16x32_bf16 v[64:67], v[136:139], v[218:221], v[64:67]
	v_mfma_f32_16x16x32_bf16 v[60:63], v[144:147], v[218:221], v[60:63]
	v_mfma_f32_16x16x32_bf16 v[52:55], v[136:139], v[226:229], v[52:55]
	v_mfma_f32_16x16x32_bf16 v[44:47], v[144:147], v[226:229], v[44:47]
	v_mfma_f32_16x16x32_bf16 v[36:39], v[136:139], v[234:237], v[36:39]
	v_mfma_f32_16x16x32_bf16 v[28:31], v[144:147], v[234:237], v[28:31]
	v_mfma_f32_16x16x32_bf16 v[20:23], v[136:139], v[242:245], v[20:23]
	v_mfma_f32_16x16x32_bf16 v[12:15], v[144:147], v[242:245], v[12:15]
	v_mfma_f32_16x16x32_bf16 v[56:59], v[158:161], v[214:217], v[56:59]
	ds_read_b128 v[132:135], v249 offset:32768
	v_mfma_f32_16x16x32_bf16 v[48:51], v[206:209], v[214:217], v[48:51]
	ds_read_b128 v[136:139], v249 offset:33792
	v_mfma_f32_16x16x32_bf16 v[40:43], v[158:161], v[222:225], v[40:43]
	ds_read_b128 v[140:143], v249 offset:34816
	v_mfma_f32_16x16x32_bf16 v[32:35], v[206:209], v[222:225], v[32:35]
	ds_read_b128 v[144:147], v249 offset:35840
	v_mfma_f32_16x16x32_bf16 v[24:27], v[158:161], v[230:233], v[24:27]
	v_mfma_f32_16x16x32_bf16 v[16:19], v[206:209], v[230:233], v[16:19]
	v_mfma_f32_16x16x32_bf16 v[8:11], v[158:161], v[238:241], v[8:11]
	v_mfma_f32_16x16x32_bf16 v[4:7], v[206:209], v[238:241], v[4:7]
	v_mfma_f32_16x16x32_bf16 v[56:59], v[174:177], v[218:221], v[56:59]
	v_mfma_f32_16x16x32_bf16 v[48:51], v[210:213], v[218:221], v[48:51]
	v_mfma_f32_16x16x32_bf16 v[40:43], v[174:177], v[226:229], v[40:43]
	v_mfma_f32_16x16x32_bf16 v[32:35], v[210:213], v[226:229], v[32:35]
	v_mfma_f32_16x16x32_bf16 v[24:27], v[174:177], v[234:237], v[24:27]
	v_mfma_f32_16x16x32_bf16 v[16:19], v[210:213], v[234:237], v[16:19]
	v_mfma_f32_16x16x32_bf16 v[8:11], v[174:177], v[242:245], v[8:11]
	v_mfma_f32_16x16x32_bf16 v[4:7], v[210:213], v[242:245], v[4:7]
	s_setprio 3
	s_barrier
	s_add_i32 s64, 0, 0x18000
	s_add_i32 s65, 0, 0x1c000
	ds_read_b128 v[158:161], v249 offset:49152
	ds_read_b128 v[174:177], v249 offset:50176
	ds_read_b128 v[206:209], v249 offset:51200
	ds_read_b128 v[210:213], v249 offset:52224
	s_add_u32 s100, s44, 0x80
	s_addc_u32 s101, s45, 0
	s_add_u32 s44, s44, 0x80000
	s_addc_u32 s45, s45, 0
	s_mov_b32 m0, s52
	ds_read_b128 v[214:217], v204 offset:32768
	ds_read_b128 v[218:221], v204 offset:33792
	ds_read_b128 v[222:225], v204 offset:34816
	ds_read_b128 v[226:229], v204 offset:35840
	ds_read_b128 v[230:233], v204 offset:36864
	ds_read_b128 v[234:237], v204 offset:37888
	ds_read_b128 v[238:241], v204 offset:38912
	ds_read_b128 v[242:245], v204 offset:39936
	global_load_lds_dwordx4 v152, s[44:45]
	s_mov_b32 m0, s53
	s_nop 0
	global_load_lds_dwordx4 v150, s[44:45]
	s_waitcnt vmcnt(8) lgkmcnt(0)
	s_setprio 0
	s_barrier
; #define PG8_STAGE(bufoff, gbase, voff) do { _Pragma("unroll") for (int _i = 0; _i < 2; ++_i) \
;         __builtin_amdgcn_global_load_lds((const unsigned*)((const char*)(gbase) + (voff)[_i]), (PG8_LAS unsigned*)(lds + (bufoff) + ldsw + _i * 8192), 16, 0, 0); } while (0)
; #define PG8_LDA(dst, b, h) do { _Pragma("unroll") for (int m = 0; m < 4; ++m) _Pragma("unroll") for (int k = 0; k < 2; ++k) dst[m][k] = *(const PG8_LAS bf16x8*)(lds + PG8_SA(b, h) + aoff + m * 2048 + k * 1024); } while (0)
; #define PG8_MMA(ai, bj, At, Bt) do { __builtin_amdgcn_s_setprio(1); _Pragma("unroll") for (int m = 0; m < 4; ++m) _Pragma("unroll") for (int n = 0; n < 2; ++n) _Pragma("unroll") for (int k = 0; k < 2; ++k) \
;         acc[ai][bj][m][n] = __builtin_amdgcn_mfma_f32_16x16x32_bf16(Bt[n][k], At[m][k], acc[ai][bj][m][n], 0, 0, 0); __builtin_amdgcn_s_setprio(0); } while (0)
; #define PG8_WAIT_V(n) asm volatile("s_waitcnt vmcnt(" #n ")" ::: "memory")
; #define PG8_WAIT_L(n) asm volatile("s_waitcnt lgkmcnt(" #n ")" ::: "memory")
; #define PG8_BAR __builtin_amdgcn_s_barrier()
; #define PG8_SCHED __builtin_amdgcn_sched_barrier(0)
; template <class Epi, class Sched, bool ALIGN_EPI = false, bool SP2 = false>
; __device__ __forceinline__ void gemm_phase(PG8_LAS unsigned char* lds, const Gemm g, const Sched& S, const Epi& E) {
;     ...
;             PG8_WAIT_V(8); PG8_WAIT_L(0); PG8_BAR; PG8_MMA(0, 0, At, B0); PG8_MMA(0, 1, At, B1); PG8_BAR; PG8_SCHED;
;             PG8_LDA(At, 1, 1); PG8_STAGE(PG8_SB(1, 0), b3, voffB); PG8_STAGE(PG8_SB(1, 1), b3 + hstep, voffB); PG8_STAGE(PG8_SA(1, 0), a3, voffA);
;             PG8_WAIT_V(8); PG8_WAIT_L(0); PG8_BAR; PG8_MMA(1, 0, At, B0); PG8_MMA(1, 1, At, B1); PG8_BAR; PG8_SCHED;
	v_mfma_f32_16x16x32_bf16 v[128:131], v[132:135], v[214:217], v[128:131]
	v_mfma_f32_16x16x32_bf16 v[124:127], v[140:143], v[214:217], v[124:127]
	v_mfma_f32_16x16x32_bf16 v[116:119], v[132:135], v[222:225], v[116:119]
	v_mfma_f32_16x16x32_bf16 v[108:111], v[140:143], v[222:225], v[108:111]
	v_mfma_f32_16x16x32_bf16 v[100:103], v[132:135], v[230:233], v[100:103]
	v_mfma_f32_16x16x32_bf16 v[92:95], v[140:143], v[230:233], v[92:95]
	v_mfma_f32_16x16x32_bf16 v[84:87], v[132:135], v[238:241], v[84:87]
	v_mfma_f32_16x16x32_bf16 v[76:79], v[140:143], v[238:241], v[76:79]
	v_mfma_f32_16x16x32_bf16 v[128:131], v[136:139], v[218:221], v[128:131]
	v_mfma_f32_16x16x32_bf16 v[124:127], v[144:147], v[218:221], v[124:127]
	v_mfma_f32_16x16x32_bf16 v[116:119], v[136:139], v[226:229], v[116:119]
	v_mfma_f32_16x16x32_bf16 v[108:111], v[144:147], v[226:229], v[108:111]
	v_mfma_f32_16x16x32_bf16 v[100:103], v[136:139], v[234:237], v[100:103]
	v_mfma_f32_16x16x32_bf16 v[92:95], v[144:147], v[234:237], v[92:95]
	v_mfma_f32_16x16x32_bf16 v[84:87], v[136:139], v[242:245], v[84:87]
	v_mfma_f32_16x16x32_bf16 v[76:79], v[144:147], v[242:245], v[76:79]
	v_mfma_f32_16x16x32_bf16 v[120:123], v[158:161], v[214:217], v[120:123]
	v_mfma_f32_16x16x32_bf16 v[112:115], v[206:209], v[214:217], v[112:115]
	v_mfma_f32_16x16x32_bf16 v[104:107], v[158:161], v[222:225], v[104:107]
	v_mfma_f32_16x16x32_bf16 v[96:99], v[206:209], v[222:225], v[96:99]
	v_mfma_f32_16x16x32_bf16 v[88:91], v[158:161], v[230:233], v[88:91]
	v_mfma_f32_16x16x32_bf16 v[80:83], v[206:209], v[230:233], v[80:83]
	v_mfma_f32_16x16x32_bf16 v[72:75], v[158:161], v[238:241], v[72:75]
	v_mfma_f32_16x16x32_bf16 v[68:71], v[206:209], v[238:241], v[68:71]
	v_mfma_f32_16x16x32_bf16 v[120:123], v[174:177], v[218:221], v[120:123]
	v_mfma_f32_16x16x32_bf16 v[112:115], v[210:213], v[218:221], v[112:115]
	v_mfma_f32_16x16x32_bf16 v[104:107], v[174:177], v[226:229], v[104:107]
	v_mfma_f32_16x16x32_bf16 v[96:99], v[210:213], v[226:229], v[96:99]
	v_mfma_f32_16x16x32_bf16 v[88:91], v[174:177], v[234:237], v[88:91]
	v_mfma_f32_16x16x32_bf16 v[80:83], v[210:213], v[234:237], v[80:83]
	v_mfma_f32_16x16x32_bf16 v[72:75], v[174:177], v[242:245], v[72:75]
	v_mfma_f32_16x16x32_bf16 v[68:71], v[210:213], v[242:245], v[68:71]
	s_setprio 3
	s_barrier
	s_add_i32 s44, s64, s46
	s_add_i32 m0, s44, 0xffffff80
	ds_read_b128 v[214:217], v204 offset:49152
	ds_read_b128 v[218:221], v204 offset:50176
	ds_read_b128 v[222:225], v204 offset:51200
	ds_read_b128 v[226:229], v204 offset:52224
	ds_read_b128 v[230:233], v204 offset:53248
	ds_read_b128 v[234:237], v204 offset:54272
	ds_read_b128 v[238:241], v204 offset:55296
	ds_read_b128 v[242:245], v204 offset:56320
	global_load_lds_dwordx4 v2, s[42:43] offset:128
	s_add_i32 m0, s44, 0x1f80
	s_add_i32 s44, s65, s46
	global_load_lds_dwordx4 v148, s[42:43] offset:128
	s_add_u32 s42, s42, 0x80080
	s_addc_u32 s43, s43, 0
	s_mov_b32 m0, s44
	s_nop 0
	global_load_lds_dwordx4 v2, s[42:43]
	s_add_i32 m0, s44, 0x2000
	s_nop 0
	global_load_lds_dwordx4 v148, s[42:43]
	s_mov_b32 m0, s54
	s_nop 0
	global_load_lds_dwordx4 v152, s[100:101]
	s_mov_b32 m0, s55
	s_nop 0
	global_load_lds_dwordx4 v150, s[100:101]
	s_waitcnt vmcnt(8) lgkmcnt(0)
	s_setprio 0
	s_barrier
	v_mfma_f32_16x16x32_bf16 v[64:67], v[132:135], v[214:217], v[64:67]
	v_mfma_f32_16x16x32_bf16 v[60:63], v[140:143], v[214:217], v[60:63]
	v_mfma_f32_16x16x32_bf16 v[52:55], v[132:135], v[222:225], v[52:55]
	v_mfma_f32_16x16x32_bf16 v[44:47], v[140:143], v[222:225], v[44:47]
	v_mfma_f32_16x16x32_bf16 v[36:39], v[132:135], v[230:233], v[36:39]
	v_mfma_f32_16x16x32_bf16 v[28:31], v[140:143], v[230:233], v[28:31]
	v_mfma_f32_16x16x32_bf16 v[20:23], v[132:135], v[238:241], v[20:23]
	v_mfma_f32_16x16x32_bf16 v[12:15], v[140:143], v[238:241], v[12:15]
	v_mfma_f32_16x16x32_bf16 v[64:67], v[136:139], v[218:221], v[64:67]
	v_mfma_f32_16x16x32_bf16 v[60:63], v[144:147], v[218:221], v[60:63]
	v_mfma_f32_16x16x32_bf16 v[52:55], v[136:139], v[226:229], v[52:55]
	v_mfma_f32_16x16x32_bf16 v[44:47], v[144:147], v[226:229], v[44:47]
	v_mfma_f32_16x16x32_bf16 v[36:39], v[136:139], v[234:237], v[36:39]
	v_mfma_f32_16x16x32_bf16 v[28:31], v[144:147], v[234:237], v[28:31]
	v_mfma_f32_16x16x32_bf16 v[20:23], v[136:139], v[242:245], v[20:23]
	v_mfma_f32_16x16x32_bf16 v[12:15], v[144:147], v[242:245], v[12:15]
	v_mfma_f32_16x16x32_bf16 v[56:59], v[158:161], v[214:217], v[56:59]
	ds_read_b128 v[132:135], v249
	v_mfma_f32_16x16x32_bf16 v[48:51], v[206:209], v[214:217], v[48:51]
	ds_read_b128 v[136:139], v249 offset:1024
	v_mfma_f32_16x16x32_bf16 v[40:43], v[158:161], v[222:225], v[40:43]
	ds_read_b128 v[140:143], v249 offset:2048
	v_mfma_f32_16x16x32_bf16 v[32:35], v[206:209], v[222:225], v[32:35]
	ds_read_b128 v[144:147], v249 offset:3072
	v_mfma_f32_16x16x32_bf16 v[24:27], v[158:161], v[230:233], v[24:27]
	v_mfma_f32_16x16x32_bf16 v[16:19], v[206:209], v[230:233], v[16:19]
	v_mfma_f32_16x16x32_bf16 v[8:11], v[158:161], v[238:241], v[8:11]
	v_mfma_f32_16x16x32_bf16 v[4:7], v[206:209], v[238:241], v[4:7]
	v_mfma_f32_16x16x32_bf16 v[56:59], v[174:177], v[218:221], v[56:59]
	v_mfma_f32_16x16x32_bf16 v[48:51], v[210:213], v[218:221], v[48:51]
	v_mfma_f32_16x16x32_bf16 v[40:43], v[174:177], v[226:229], v[40:43]
	v_mfma_f32_16x16x32_bf16 v[32:35], v[210:213], v[226:229], v[32:35]
	v_mfma_f32_16x16x32_bf16 v[24:27], v[174:177], v[234:237], v[24:27]
	v_mfma_f32_16x16x32_bf16 v[16:19], v[210:213], v[234:237], v[16:19]
	v_mfma_f32_16x16x32_bf16 v[8:11], v[174:177], v[242:245], v[8:11]
	v_mfma_f32_16x16x32_bf16 v[4:7], v[210:213], v[242:245], v[4:7]
	s_setprio 3
	s_barrier
	s_add_i32 s63, s63, 2
	s_add_u32 s40, s40, 0x100
	s_addc_u32 s41, s41, 0
	s_add_u32 s35, s35, 0x100
	s_addc_u32 s62, s62, 0
	s_cmp_gt_u32 s63, 29
	s_cbranch_scc0 .LBB0_674
	s_branch .Lpost_p4
	.p2align 6
	s_nop 0

; #define PG8_BAR __builtin_amdgcn_s_barrier()
;     __device__ __forceinline__ void operator()(const f32x4 (&acc)[2][2][4][2], const Unit& u, int wr, int wc, int fr, int fq) const {
;     ...
;         } else if (u.aux == 1) {
;             float rs[2][4]; row_rstd8(tab, wr * 64 + fr, rs);
;             if (wc == 0 && fq == 0) {
; #pragma unroll
;                 for (int ai = 0; ai < 2; ++ai)
; #pragma unroll
;                     for (int m = 0; m < 4; ++m) { float* gp = G + (size_t)(row0 + ai * HALF + m * 16) * 8;
;                         *(f32x4*)gp = acc[ai][0][m][0] * rs[ai][m]; *(f32x4*)(gp + 4) = acc[ai][0][m][1] * rs[ai][m]; } }
; template <class Epi, class Sched, bool ALIGN_EPI = false, bool SP2 = false>
; __device__ __forceinline__ void gemm_phase(PG8_LAS unsigned char* lds, const Gemm g, const Sched& S, const Epi& E) {
;     ...
;         if constexpr (ALIGN_EPI) { if (wr == 0) PG8_BAR; }
.Lpost_p4:
	s_and_b64 vcc, exec, s[30:31]
	s_cbranch_vccz .LBB0_677
	s_barrier
.LBB0_677:
	s_mov_b32 s32, 0
	v_lshl_add_u32 v158, s61, 8, v1
	s_mov_b64 s[44:45], -1
	s_mov_b64 s[40:41], 0
	s_cmp_lt_i32 s60, 1
	s_mov_b64 s[42:43], 0
	s_cbranch_scc1 .LBB0_683
	s_cmp_eq_u32 s60, 1
	s_mov_b64 s[42:43], -1
	s_cbranch_scc0 .LBB0_682
	s_and_saveexec_b64 s[42:43], s[0:1]
	s_cbranch_execz .LBB0_681
	ds_read2_b32 v[136:137], v178 offset0:160 offset1:176
	ds_read2_b32 v[138:139], v178 offset0:128 offset1:144
	ds_read2_b32 v[140:141], v178 offset1:16
	ds_read2_b32 v[142:143], v178 offset0:32 offset1:48
	v_ashrrev_i32_e32 v159, 31, v158
	v_lshlrev_b64 v[132:133], 5, v[158:159]
	v_lshl_add_u64 v[144:145], s[12:13], 0, v[132:133]
	s_waitcnt lgkmcnt(0)
	v_pk_mul_f32 v[134:135], v[130:131], v[140:141] op_sel_hi:[1,0]
	v_pk_mul_f32 v[132:133], v[128:129], v[140:141] op_sel_hi:[1,0]
	global_store_dwordx4 v[144:145], v[132:135], off
	s_mov_b64 s[44:45], 0x1000
	s_nop 0
	v_pk_mul_f32 v[134:135], v[126:127], v[140:141] op_sel_hi:[1,0]
	v_pk_mul_f32 v[132:133], v[124:125], v[140:141] op_sel_hi:[1,0]
	global_store_dwordx4 v[144:145], v[132:135], off offset:16
	v_mov_b32_e32 v140, v141
	s_nop 0
	v_or_b32_e32 v132, 16, v158
	v_ashrrev_i32_e32 v133, 31, v132
	v_lshlrev_b64 v[132:133], 5, v[132:133]
	v_lshl_add_u64 v[146:147], s[12:13], 0, v[132:133]
	v_pk_mul_f32 v[134:135], v[118:119], v[140:141] op_sel_hi:[1,0]
	v_pk_mul_f32 v[132:133], v[116:117], v[140:141] op_sel_hi:[1,0]
	global_store_dwordx4 v[146:147], v[132:135], off
	s_nop 1
	v_pk_mul_f32 v[134:135], v[110:111], v[140:141] op_sel_hi:[1,0]
	v_pk_mul_f32 v[132:133], v[108:109], v[140:141] op_sel_hi:[1,0]
	global_store_dwordx4 v[146:147], v[132:135], off offset:16
	s_nop 1
	v_or_b32_e32 v132, 32, v158
	v_ashrrev_i32_e32 v133, 31, v132
	v_lshlrev_b64 v[132:133], 5, v[132:133]
	v_lshl_add_u64 v[140:141], s[12:13], 0, v[132:133]
	v_pk_mul_f32 v[134:135], v[102:103], v[142:143] op_sel_hi:[1,0]
	v_pk_mul_f32 v[132:133], v[100:101], v[142:143] op_sel_hi:[1,0]
	global_store_dwordx4 v[140:141], v[132:135], off
	s_nop 1
	v_pk_mul_f32 v[134:135], v[94:95], v[142:143] op_sel_hi:[1,0]
	v_pk_mul_f32 v[132:133], v[92:93], v[142:143] op_sel_hi:[1,0]
	global_store_dwordx4 v[140:141], v[132:135], off offset:16
	v_mov_b32_e32 v142, v143
	s_nop 0
	v_or_b32_e32 v132, 48, v158
	v_ashrrev_i32_e32 v133, 31, v132
	v_lshlrev_b64 v[132:133], 5, v[132:133]
	v_lshl_add_u64 v[140:141], s[12:13], 0, v[132:133]
	v_pk_mul_f32 v[134:135], v[86:87], v[142:143] op_sel_hi:[1,0]
	v_pk_mul_f32 v[132:133], v[84:85], v[142:143] op_sel_hi:[1,0]
	global_store_dwordx4 v[140:141], v[132:135], off
	s_nop 1
	v_pk_mul_f32 v[134:135], v[78:79], v[142:143] op_sel_hi:[1,0]
	v_pk_mul_f32 v[132:133], v[76:77], v[142:143] op_sel_hi:[1,0]
	v_add_co_u32_e32 v142, vcc, s33, v144
	global_store_dwordx4 v[140:141], v[132:135], off offset:16
	s_nop 0
	v_addc_co_u32_e32 v143, vcc, 0, v145, vcc
	v_pk_mul_f32 v[134:135], v[66:67], v[138:139] op_sel_hi:[1,0]
	v_pk_mul_f32 v[132:133], v[64:65], v[138:139] op_sel_hi:[1,0]
	v_lshl_add_u64 v[140:141], v[144:145], 0, s[44:45]
	global_store_dwordx4 v[142:143], v[132:135], off
	s_mov_b64 s[44:45], 0x1200
	s_nop 0
	v_pk_mul_f32 v[134:135], v[62:63], v[138:139] op_sel_hi:[1,0]
	v_pk_mul_f32 v[132:133], v[60:61], v[138:139] op_sel_hi:[1,0]
	v_mov_b32_e32 v138, v139
	global_store_dwordx4 v[140:141], v[132:135], off offset:16
	v_lshl_add_u64 v[140:141], v[144:145], 0, s[44:45]
	s_mov_b64 s[44:45], 0x1400
	v_pk_mul_f32 v[134:135], v[54:55], v[138:139] op_sel_hi:[1,0]
	v_pk_mul_f32 v[132:133], v[52:53], v[138:139] op_sel_hi:[1,0]
	global_store_dwordx4 v[142:143], v[132:135], off offset:512
	s_nop 1
	v_pk_mul_f32 v[134:135], v[46:47], v[138:139] op_sel_hi:[1,0]
	v_pk_mul_f32 v[132:133], v[44:45], v[138:139] op_sel_hi:[1,0]
	global_store_dwordx4 v[140:141], v[132:135], off offset:16
	v_lshl_add_u64 v[138:139], v[144:145], 0, s[44:45]
	s_mov_b64 s[44:45], 0x1600
	v_pk_mul_f32 v[134:135], v[38:39], v[136:137] op_sel_hi:[1,0]
	v_pk_mul_f32 v[132:133], v[36:37], v[136:137] op_sel_hi:[1,0]
	global_store_dwordx4 v[142:143], v[132:135], off offset:1024
	s_nop 1
	v_pk_mul_f32 v[134:135], v[30:31], v[136:137] op_sel_hi:[1,0]
	v_pk_mul_f32 v[132:133], v[28:29], v[136:137] op_sel_hi:[1,0]
	v_mov_b32_e32 v136, v137
	global_store_dwordx4 v[138:139], v[132:135], off offset:16
	v_lshl_add_u64 v[138:139], v[144:145], 0, s[44:45]
	s_nop 0
	v_pk_mul_f32 v[134:135], v[22:23], v[136:137] op_sel_hi:[1,0]
	v_pk_mul_f32 v[132:133], v[20:21], v[136:137] op_sel_hi:[1,0]
	global_store_dwordx4 v[142:143], v[132:135], off offset:1536
	s_nop 1
	v_pk_mul_f32 v[134:135], v[14:15], v[136:137] op_sel_hi:[1,0]
	v_pk_mul_f32 v[132:133], v[12:13], v[136:137] op_sel_hi:[1,0]
	global_store_dwordx4 v[138:139], v[132:135], off offset:16

; __device__ __forceinline__ unsigned cvt_pk_bf16(float lo, float hi) { unsigned r; asm volatile("v_cvt_pk_bf16_f32 %0, %1, %2" : "=v"(r) : "v"(lo), "v"(hi)); return r; }
;     __device__ __forceinline__ void operator()(const f32x4 (&acc)[2][2][4][2], const Unit& u, int wr, int wc, int fr, int fq) const {
;     ...
;             const int tb = u.pn * BM + wc * 32 + 8 * fq; float rt[16];
; #pragma unroll
;             for (int j = 0; j < 16; ++j) rt[j] = tab[wc * 32 + 8 * fq + 128 * (j >> 3) + (j & 7)];
;             const int col0 = tb;
; #pragma unroll
;             for (int ai = 0; ai < 2; ++ai)
; #pragma unroll
;                 for (int m = 0; m < 4; ++m) { bf16_t* rowp = ZT + (size_t)(row0 + ai * HALF + m * 16) * ldt + col0;
; #pragma unroll
;                     for (int bj = 0; bj < 2; ++bj) { const f32x4 v0 = acc[ai][bj][m][0], v1 = acc[ai][bj][m][1];
;                         u32x4 w; w.x = cvt_pk_bf16(v0[0] * rt[8 * bj], v0[1] * rt[8 * bj + 1]); w.y = cvt_pk_bf16(v0[2] * rt[8 * bj + 2], v0[3] * rt[8 * bj + 3]);
;                         w.z = cvt_pk_bf16(v1[0] * rt[8 * bj + 4], v1[1] * rt[8 * bj + 5]); w.w = cvt_pk_bf16(v1[2] * rt[8 * bj + 6], v1[3] * rt[8 * bj + 7]);
;                         *(u32x4*)(rowp + bj * HALF) = w; } }
.LBB0_685:
	s_andn2_b64 vcc, exec, s[42:43]
	v_or_b32_e32 v174, 16, v158
	v_or_b32_e32 v162, 32, v158
	v_or_b32_e32 v160, 48, v158
	s_cbranch_vccnz .LBB0_688
	s_mov_b32 s32, 1
	ds_read_b128 v[144:147], v179
	ds_read_b128 v[140:143], v180
	ds_read_b128 v[136:139], v181
	ds_read_b128 v[132:135], v182
	v_ashrrev_i32_e32 v159, 31, v158
	s_waitcnt lgkmcnt(0)
	v_mul_f32_e32 v161, v129, v145
	v_lshl_or_b32 v164, s38, 8, v203
	v_lshlrev_b64 v[170:171], 14, v[158:159]
	v_mul_f32_e32 v159, v128, v144
	v_cvt_pk_bf16_f32 v206, v159, v161
	v_mul_f32_e32 v161, v131, v147
	v_ashrrev_i32_e32 v165, 31, v164
	v_mul_f32_e32 v159, v130, v146
	v_cvt_pk_bf16_f32 v207, v159, v161
	v_mul_f32_e32 v161, v125, v141
	v_lshl_add_u64 v[170:171], s[28:29], 0, v[170:171]
	v_lshlrev_b64 v[164:165], 1, v[164:165]
	v_mul_f32_e32 v159, v124, v140
	v_cvt_pk_bf16_f32 v208, v159, v161
	v_mul_f32_e32 v161, v127, v143
	v_lshl_add_u64 v[176:177], v[170:171], 0, v[164:165]
	v_mul_f32_e32 v159, v126, v142
	v_cvt_pk_bf16_f32 v209, v159, v161
	v_mul_f32_e32 v161, v121, v137
	global_store_dwordx4 v[176:177], v[206:209], off
	v_mul_f32_e32 v159, v120, v136
	v_ashrrev_i32_e32 v175, 31, v174
	v_cvt_pk_bf16_f32 v206, v159, v161
	v_mul_f32_e32 v161, v123, v139
	v_mul_f32_e32 v159, v122, v138
	v_cvt_pk_bf16_f32 v207, v159, v161
	v_mul_f32_e32 v161, v113, v133
	v_mul_f32_e32 v159, v112, v132
	v_cvt_pk_bf16_f32 v208, v159, v161
	v_mul_f32_e32 v161, v115, v135
	v_mul_f32_e32 v159, v114, v134
	v_cvt_pk_bf16_f32 v209, v159, v161
	v_mul_f32_e32 v161, v117, v145
	global_store_dwordx4 v[176:177], v[206:209], off offset:256
	v_mul_f32_e32 v159, v116, v144
	v_lshlrev_b64 v[170:171], 14, v[174:175]
	v_cvt_pk_bf16_f32 v206, v159, v161
	v_mul_f32_e32 v161, v119, v147
	v_mul_f32_e32 v159, v118, v146
	v_cvt_pk_bf16_f32 v207, v159, v161
	v_mul_f32_e32 v161, v109, v141
	v_lshl_add_u64 v[170:171], s[28:29], 0, v[170:171]
	v_mul_f32_e32 v159, v108, v140
	v_cvt_pk_bf16_f32 v208, v159, v161
	v_mul_f32_e32 v161, v111, v143
	v_lshl_add_u64 v[170:171], v[170:171], 0, v[164:165]
	v_mul_f32_e32 v159, v110, v142
	v_cvt_pk_bf16_f32 v209, v159, v161
	v_mul_f32_e32 v161, v105, v137
	global_store_dwordx4 v[170:171], v[206:209], off
	v_mul_f32_e32 v159, v104, v136
	v_ashrrev_i32_e32 v163, 31, v162
	v_cvt_pk_bf16_f32 v206, v159, v161
	v_mul_f32_e32 v161, v107, v139
	v_mul_f32_e32 v159, v106, v138
	v_cvt_pk_bf16_f32 v207, v159, v161
	v_mul_f32_e32 v161, v97, v133
	v_mul_f32_e32 v159, v96, v132
	v_cvt_pk_bf16_f32 v208, v159, v161
	v_mul_f32_e32 v161, v99, v135
	v_mul_f32_e32 v159, v98, v134
	v_cvt_pk_bf16_f32 v209, v159, v161
	v_mul_f32_e32 v161, v101, v145
	global_store_dwordx4 v[170:171], v[206:209], off offset:256
	v_mul_f32_e32 v159, v100, v144
	v_lshlrev_b64 v[170:171], 14, v[162:163]
	v_cvt_pk_bf16_f32 v206, v159, v161
	v_mul_f32_e32 v161, v103, v147
	v_mul_f32_e32 v159, v102, v146
	v_cvt_pk_bf16_f32 v207, v159, v161
	v_mul_f32_e32 v161, v93, v141
	v_lshl_add_u64 v[170:171], s[28:29], 0, v[170:171]
	v_mul_f32_e32 v159, v92, v140
	v_cvt_pk_bf16_f32 v208, v159, v161
	v_mul_f32_e32 v161, v95, v143
	v_lshl_add_u64 v[170:171], v[170:171], 0, v[164:165]
	v_mul_f32_e32 v159, v94, v142
	v_cvt_pk_bf16_f32 v209, v159, v161
	v_mul_f32_e32 v161, v89, v137
	global_store_dwordx4 v[170:171], v[206:209], off
	v_mul_f32_e32 v159, v88, v136
	s_mov_b32 s35, 0x200000
	v_cvt_pk_bf16_f32 v206, v159, v161
	v_mul_f32_e32 v161, v91, v139
	v_mul_f32_e32 v159, v90, v138
	v_cvt_pk_bf16_f32 v207, v159, v161
	v_mul_f32_e32 v161, v81, v133
	v_mul_f32_e32 v159, v80, v132
	v_cvt_pk_bf16_f32 v208, v159, v161
	v_mul_f32_e32 v161, v83, v135
	v_mul_f32_e32 v159, v82, v134
	v_cvt_pk_bf16_f32 v209, v159, v161
	v_ashrrev_i32_e32 v161, 31, v160
	global_store_dwordx4 v[170:171], v[206:209], off offset:256
	v_lshlrev_b64 v[170:171], 14, v[160:161]
	v_mul_f32_e32 v159, v84, v144
	v_mul_f32_e32 v161, v85, v145
	v_cvt_pk_bf16_f32 v206, v159, v161
	v_mul_f32_e32 v159, v86, v146
	v_mul_f32_e32 v161, v87, v147
	v_cvt_pk_bf16_f32 v207, v159, v161
	v_mul_f32_e32 v159, v76, v140
	v_mul_f32_e32 v161, v77, v141
	v_lshl_add_u64 v[170:171], s[28:29], 0, v[170:171]
	v_cvt_pk_bf16_f32 v208, v159, v161
	v_mul_f32_e32 v159, v78, v142
	v_mul_f32_e32 v161, v79, v143
	v_lshl_add_u64 v[164:165], v[170:171], 0, v[164:165]
	v_cvt_pk_bf16_f32 v209, v159, v161
	v_mul_f32_e32 v159, v72, v136
	v_mul_f32_e32 v161, v73, v137
	global_store_dwordx4 v[164:165], v[206:209], off
	v_add_co_u32_e32 v170, vcc, s35, v176
	s_nop 0
	v_cvt_pk_bf16_f32 v206, v159, v161
	v_mul_f32_e32 v159, v74, v138
	v_mul_f32_e32 v161, v75, v139
	v_cvt_pk_bf16_f32 v207, v159, v161
; __device__ __forceinline__ unsigned cvt_pk_bf16(float lo, float hi) { unsigned r; asm volatile("v_cvt_pk_bf16_f32 %0, %1, %2" : "=v"(r) : "v"(lo), "v"(hi)); return r; }
;     __device__ __forceinline__ void operator()(const f32x4 (&acc)[2][2][4][2], const Unit& u, int wr, int wc, int fr, int fq) const {
;     ...
;             for (int ai = 0; ai < 2; ++ai)
; #pragma unroll
;                 for (int m = 0; m < 4; ++m) { bf16_t* rowp = ZT + (size_t)(row0 + ai * HALF + m * 16) * ldt + col0;
; #pragma unroll
;                     for (int bj = 0; bj < 2; ++bj) { const f32x4 v0 = acc[ai][bj][m][0], v1 = acc[ai][bj][m][1];
;                         u32x4 w; w.x = cvt_pk_bf16(v0[0] * rt[8 * bj], v0[1] * rt[8 * bj + 1]); w.y = cvt_pk_bf16(v0[2] * rt[8 * bj + 2], v0[3] * rt[8 * bj + 3]);
;                         w.z = cvt_pk_bf16(v1[0] * rt[8 * bj + 4], v1[1] * rt[8 * bj + 5]); w.w = cvt_pk_bf16(v1[2] * rt[8 * bj + 6], v1[3] * rt[8 * bj + 7]);
;                         *(u32x4*)(rowp + bj * HALF) = w; } }
	v_mul_f32_e32 v159, v68, v132
	v_mul_f32_e32 v161, v69, v133
	v_cvt_pk_bf16_f32 v208, v159, v161
	v_mul_f32_e32 v159, v70, v134
	v_mul_f32_e32 v161, v71, v135
	v_cvt_pk_bf16_f32 v209, v159, v161
	v_mul_f32_e32 v159, v64, v144
	v_mul_f32_e32 v161, v65, v145
	global_store_dwordx4 v[164:165], v[206:209], off offset:256
	v_addc_co_u32_e32 v171, vcc, 0, v177, vcc
	s_nop 0
	v_cvt_pk_bf16_f32 v206, v159, v161
	v_mul_f32_e32 v159, v66, v146
	v_mul_f32_e32 v161, v67, v147
	v_cvt_pk_bf16_f32 v207, v159, v161
	v_mul_f32_e32 v159, v60, v140
	v_mul_f32_e32 v161, v61, v141
	v_cvt_pk_bf16_f32 v208, v159, v161
	v_mul_f32_e32 v159, v62, v142
	v_mul_f32_e32 v161, v63, v143
	v_cvt_pk_bf16_f32 v209, v159, v161
	v_mul_f32_e32 v159, v56, v136
	v_mul_f32_e32 v161, v57, v137
	global_store_dwordx4 v[170:171], v[206:209], off
	s_mov_b64 s[40:41], 0x200000
	v_lshl_add_u64 v[164:165], v[176:177], 0, s[40:41]
	v_cvt_pk_bf16_f32 v206, v159, v161
	v_mul_f32_e32 v159, v58, v138
	v_mul_f32_e32 v161, v59, v139
	v_cvt_pk_bf16_f32 v207, v159, v161
	v_mul_f32_e32 v159, v48, v132
	v_mul_f32_e32 v161, v49, v133
	v_cvt_pk_bf16_f32 v208, v159, v161
	v_mul_f32_e32 v159, v50, v134
	v_mul_f32_e32 v161, v51, v135
	v_cvt_pk_bf16_f32 v209, v159, v161
	v_mul_f32_e32 v159, v52, v144
	v_mul_f32_e32 v161, v53, v145
	global_store_dwordx4 v[164:165], v[206:209], off offset:256
	s_mov_b32 s35, 0x240000
	v_add_co_u32_e32 v170, vcc, s35, v176
	v_cvt_pk_bf16_f32 v206, v159, v161
	v_mul_f32_e32 v159, v54, v146
	v_mul_f32_e32 v161, v55, v147
	v_cvt_pk_bf16_f32 v207, v159, v161
	v_mul_f32_e32 v159, v44, v140
	v_mul_f32_e32 v161, v45, v141
	v_cvt_pk_bf16_f32 v208, v159, v161
	v_mul_f32_e32 v159, v46, v142
	v_mul_f32_e32 v161, v47, v143
	v_cvt_pk_bf16_f32 v209, v159, v161
	v_addc_co_u32_e32 v171, vcc, 0, v177, vcc
	v_mul_f32_e32 v159, v40, v136
	v_mul_f32_e32 v161, v41, v137
	global_store_dwordx4 v[170:171], v[206:209], off
	s_mov_b64 s[40:41], 0x240000
	v_lshl_add_u64 v[164:165], v[176:177], 0, s[40:41]
	v_cvt_pk_bf16_f32 v206, v159, v161
	v_mul_f32_e32 v159, v42, v138
	v_mul_f32_e32 v161, v43, v139
	v_cvt_pk_bf16_f32 v207, v159, v161
	v_mul_f32_e32 v159, v32, v132
	v_mul_f32_e32 v161, v33, v133
	v_cvt_pk_bf16_f32 v208, v159, v161
	v_mul_f32_e32 v159, v34, v134
	v_mul_f32_e32 v161, v35, v135
	v_cvt_pk_bf16_f32 v209, v159, v161
	v_mul_f32_e32 v159, v36, v144
	v_mul_f32_e32 v161, v37, v145
	global_store_dwordx4 v[164:165], v[206:209], off offset:256
	s_mov_b32 s35, 0x280000
	v_add_co_u32_e32 v170, vcc, s35, v176
	v_cvt_pk_bf16_f32 v206, v159, v161
	v_mul_f32_e32 v159, v38, v146
	v_mul_f32_e32 v161, v39, v147
	v_cvt_pk_bf16_f32 v207, v159, v161
	v_mul_f32_e32 v159, v28, v140
	v_mul_f32_e32 v161, v29, v141
	v_cvt_pk_bf16_f32 v208, v159, v161
	v_mul_f32_e32 v159, v30, v142
	v_mul_f32_e32 v161, v31, v143
	v_cvt_pk_bf16_f32 v209, v159, v161
	v_addc_co_u32_e32 v171, vcc, 0, v177, vcc
	v_mul_f32_e32 v159, v24, v136
	v_mul_f32_e32 v161, v25, v137
	s_mov_b64 s[40:41], 0x280000
	global_store_dwordx4 v[170:171], v[206:209], off
	v_lshl_add_u64 v[164:165], v[176:177], 0, s[40:41]
	v_mul_f32_e32 v144, v20, v144
	v_cvt_pk_bf16_f32 v206, v159, v161
	v_mul_f32_e32 v159, v26, v138
	v_mul_f32_e32 v161, v27, v139
	v_cvt_pk_bf16_f32 v207, v159, v161
	v_mul_f32_e32 v159, v16, v132
	v_mul_f32_e32 v161, v17, v133
	v_mul_f32_e32 v145, v21, v145
	v_cvt_pk_bf16_f32 v208, v159, v161
	v_mul_f32_e32 v159, v18, v134
	v_mul_f32_e32 v161, v19, v135
	v_cvt_pk_bf16_f32 v209, v159, v161
	global_store_dwordx4 v[164:165], v[206:209], off offset:256
	v_cvt_pk_bf16_f32 v144, v144, v145
	v_mul_f32_e32 v145, v22, v146
	v_mul_f32_e32 v146, v23, v147
	v_mul_f32_e32 v140, v12, v140
	v_cvt_pk_bf16_f32 v145, v145, v146
	v_mul_f32_e32 v141, v13, v141
	v_cvt_pk_bf16_f32 v146, v140, v141
	v_mul_f32_e32 v140, v14, v142
	s_mov_b32 s35, 0x2c0000
	v_mul_f32_e32 v141, v15, v143
	v_cvt_pk_bf16_f32 v147, v140, v141
	v_add_co_u32_e32 v140, vcc, s35, v176
	s_mov_b64 s[40:41], 0x2c0000
	s_nop 0
	v_addc_co_u32_e32 v141, vcc, 0, v177, vcc
	v_mul_f32_e32 v136, v8, v136
	v_mul_f32_e32 v137, v9, v137
	v_lshl_add_u64 v[164:165], v[176:177], 0, s[40:41]
	global_store_dwordx4 v[140:141], v[144:147], off
	v_cvt_pk_bf16_f32 v136, v136, v137
	v_mul_f32_e32 v137, v10, v138
	v_mul_f32_e32 v138, v11, v139
	v_mul_f32_e32 v132, v4, v132
	v_mul_f32_e32 v133, v5, v133
	v_cvt_pk_bf16_f32 v137, v137, v138
	v_cvt_pk_bf16_f32 v138, v132, v133
	v_mul_f32_e32 v132, v6, v134
	v_mul_f32_e32 v133, v7, v135
	v_cvt_pk_bf16_f32 v139, v132, v133
	global_store_dwordx4 v[164:165], v[136:139], off offset:256
	s_cbranch_execz .LBB0_689

; __device__ __forceinline__ unsigned cvt_pk_bf16(float lo, float hi) { unsigned r; asm volatile("v_cvt_pk_bf16_f32 %0, %1, %2" : "=v"(r) : "v"(lo), "v"(hi)); return r; }
;     __device__ __forceinline__ void operator()(const f32x4 (&acc)[2][2][4][2], const Unit& u, int wr, int wc, int fr, int fq) const {
;     ...
;             float rs[2][4]; row_rstd8(tab, wr * 64 + fr, rs);
;             const int col0 = u.pn * BM + wc * 64 + 8 * fq;
; #pragma unroll
;             for (int ai = 0; ai < 2; ++ai)
; #pragma unroll
;                 for (int m = 0; m < 4; ++m) { bf16_t* rowp = Z + (size_t)(row0 + ai * HALF + m * 16) * ldz + col0; const float r = rs[ai][m];
; #pragma unroll
;                     for (int bj = 0; bj < 2; ++bj) { const f32x4 v0 = acc[ai][bj][m][0] * r, v1 = acc[ai][bj][m][1] * r;
;                         u32x4 w; w.x = cvt_pk_bf16(v0[0], v0[1]); w.y = cvt_pk_bf16(v0[2], v0[3]); w.z = cvt_pk_bf16(v1[0], v1[1]); w.w = cvt_pk_bf16(v1[2], v1[3]);
;                         *(u32x4*)(rowp + bj * 32) = w; } }
.LBB0_689:
	s_mov_b32 s32, 1
	s_nop 0
	v_lshl_or_b32 v136, s38, 8, v183
	ds_read2_b32 v[140:141], v178 offset1:16
	ds_read2_b32 v[142:143], v178 offset0:32 offset1:48
	ds_read2_b32 v[138:139], v178 offset0:128 offset1:144
	ds_read2_b32 v[132:133], v178 offset0:160 offset1:176
	v_ashrrev_i32_e32 v137, 31, v136
	v_mov_b64_e32 v[134:135], s[10:11]
	v_mad_i64_i32 v[144:145], s[40:41], v158, s25, v[134:135]
	v_lshlrev_b64 v[136:137], 1, v[136:137]
	v_lshl_add_u64 v[144:145], v[144:145], 0, v[136:137]
	s_waitcnt lgkmcnt(0)
	v_pk_mul_f32 v[130:131], v[130:131], v[140:141] op_sel_hi:[1,0]
	v_pk_mul_f32 v[128:129], v[128:129], v[140:141] op_sel_hi:[1,0]
	v_pk_mul_f32 v[146:147], v[126:127], v[140:141] op_sel_hi:[1,0]
	v_pk_mul_f32 v[126:127], v[124:125], v[140:141] op_sel_hi:[1,0]
	v_cvt_pk_bf16_f32 v124, v128, v129
	v_cvt_pk_bf16_f32 v125, v130, v131
	v_pk_mul_f32 v[122:123], v[122:123], v[140:141] op_sel_hi:[1,0]
	v_cvt_pk_bf16_f32 v126, v126, v127
	v_cvt_pk_bf16_f32 v127, v146, v147
	global_store_dwordx4 v[144:145], v[124:127], off
	v_pk_mul_f32 v[120:121], v[120:121], v[140:141] op_sel_hi:[1,0]
	v_pk_mul_f32 v[100:101], v[100:101], v[142:143] op_sel_hi:[1,0]
	v_pk_mul_f32 v[124:125], v[114:115], v[140:141] op_sel_hi:[1,0]
	v_pk_mul_f32 v[114:115], v[112:113], v[140:141] op_sel_hi:[1,0]
	v_cvt_pk_bf16_f32 v112, v120, v121
	v_cvt_pk_bf16_f32 v113, v122, v123
	v_pk_mul_f32 v[90:91], v[90:91], v[142:143] op_sel_hi:[1,0]
	v_cvt_pk_bf16_f32 v114, v114, v115
	v_cvt_pk_bf16_f32 v115, v124, v125
	global_store_dwordx4 v[144:145], v[112:115], off offset:64
	v_pk_mul_f32 v[88:89], v[88:89], v[142:143] op_sel_hi:[1,0]
	v_pk_mul_f32 v[66:67], v[66:67], v[138:139] op_sel_hi:[1,0]
	v_mad_i64_i32 v[112:113], s[40:41], v174, s25, v[134:135]
	v_mov_b32_e32 v114, v141
	v_lshl_add_u64 v[112:113], v[112:113], 0, v[136:137]
	v_pk_mul_f32 v[118:119], v[118:119], v[114:115] op_sel_hi:[1,0]
	v_pk_mul_f32 v[116:117], v[116:117], v[114:115] op_sel_hi:[1,0]
	v_pk_mul_f32 v[120:121], v[110:111], v[114:115] op_sel_hi:[1,0]
	v_pk_mul_f32 v[110:111], v[108:109], v[114:115] op_sel_hi:[1,0]
	v_cvt_pk_bf16_f32 v108, v116, v117
	v_cvt_pk_bf16_f32 v109, v118, v119
	v_pk_mul_f32 v[106:107], v[106:107], v[114:115] op_sel_hi:[1,0]
	v_cvt_pk_bf16_f32 v110, v110, v111
	v_cvt_pk_bf16_f32 v111, v120, v121
	global_store_dwordx4 v[112:113], v[108:111], off
	v_pk_mul_f32 v[104:105], v[104:105], v[114:115] op_sel_hi:[1,0]
	v_pk_mul_f32 v[64:65], v[64:65], v[138:139] op_sel_hi:[1,0]
	v_pk_mul_f32 v[108:109], v[98:99], v[114:115] op_sel_hi:[1,0]
	v_pk_mul_f32 v[98:99], v[96:97], v[114:115] op_sel_hi:[1,0]
	v_cvt_pk_bf16_f32 v96, v104, v105
	v_cvt_pk_bf16_f32 v97, v106, v107
	v_pk_mul_f32 v[56:57], v[56:57], v[138:139] op_sel_hi:[1,0]
	v_cvt_pk_bf16_f32 v98, v98, v99
	v_cvt_pk_bf16_f32 v99, v108, v109
	global_store_dwordx4 v[112:113], v[96:99], off offset:64
	v_pk_mul_f32 v[58:59], v[58:59], v[138:139] op_sel_hi:[1,0]
	v_pk_mul_f32 v[36:37], v[36:37], v[132:133] op_sel_hi:[1,0]
	v_mad_i64_i32 v[96:97], s[40:41], v162, s25, v[134:135]
	v_lshl_add_u64 v[96:97], v[96:97], 0, v[136:137]
	v_pk_mul_f32 v[98:99], v[102:103], v[142:143] op_sel_hi:[1,0]
	v_pk_mul_f32 v[102:103], v[94:95], v[142:143] op_sel_hi:[1,0]
	v_pk_mul_f32 v[94:95], v[92:93], v[142:143] op_sel_hi:[1,0]
	v_cvt_pk_bf16_f32 v92, v100, v101
	v_cvt_pk_bf16_f32 v93, v98, v99
	v_pk_mul_f32 v[24:25], v[24:25], v[132:133] op_sel_hi:[1,0]
	v_cvt_pk_bf16_f32 v94, v94, v95
	v_cvt_pk_bf16_f32 v95, v102, v103
	global_store_dwordx4 v[96:97], v[92:95], off
	v_pk_mul_f32 v[26:27], v[26:27], v[132:133] op_sel_hi:[1,0]
	s_nop 0
	v_pk_mul_f32 v[92:93], v[82:83], v[142:143] op_sel_hi:[1,0]
	v_pk_mul_f32 v[82:83], v[80:81], v[142:143] op_sel_hi:[1,0]
	v_cvt_pk_bf16_f32 v80, v88, v89
	v_cvt_pk_bf16_f32 v81, v90, v91
	s_nop 0
	v_cvt_pk_bf16_f32 v82, v82, v83
	v_cvt_pk_bf16_f32 v83, v92, v93
	global_store_dwordx4 v[96:97], v[80:83], off offset:64
	s_nop 1
	v_mad_i64_i32 v[80:81], s[40:41], v160, s25, v[134:135]
	v_mov_b32_e32 v82, v143
	v_lshl_add_u64 v[80:81], v[80:81], 0, v[136:137]
	v_pk_mul_f32 v[86:87], v[86:87], v[82:83] op_sel_hi:[1,0]
	v_pk_mul_f32 v[84:85], v[84:85], v[82:83] op_sel_hi:[1,0]
	v_pk_mul_f32 v[88:89], v[78:79], v[82:83] op_sel_hi:[1,0]
	v_pk_mul_f32 v[78:79], v[76:77], v[82:83] op_sel_hi:[1,0]
	v_cvt_pk_bf16_f32 v76, v84, v85
; __device__ __forceinline__ unsigned cvt_pk_bf16(float lo, float hi) { unsigned r; asm volatile("v_cvt_pk_bf16_f32 %0, %1, %2" : "=v"(r) : "v"(lo), "v"(hi)); return r; }
;     __device__ __forceinline__ void operator()(const f32x4 (&acc)[2][2][4][2], const Unit& u, int wr, int wc, int fr, int fq) const {
;     ...
;             for (int ai = 0; ai < 2; ++ai)
; #pragma unroll
;                 for (int m = 0; m < 4; ++m) { bf16_t* rowp = Z + (size_t)(row0 + ai * HALF + m * 16) * ldz + col0; const float r = rs[ai][m];
; #pragma unroll
;                     for (int bj = 0; bj < 2; ++bj) { const f32x4 v0 = acc[ai][bj][m][0] * r, v1 = acc[ai][bj][m][1] * r;
;                         u32x4 w; w.x = cvt_pk_bf16(v0[0], v0[1]); w.y = cvt_pk_bf16(v0[2], v0[3]); w.z = cvt_pk_bf16(v1[0], v1[1]); w.w = cvt_pk_bf16(v1[2], v1[3]);
;                         *(u32x4*)(rowp + bj * 32) = w; } }
	v_cvt_pk_bf16_f32 v77, v86, v87
	v_pk_mul_f32 v[72:73], v[72:73], v[82:83] op_sel_hi:[1,0]
	v_cvt_pk_bf16_f32 v78, v78, v79
	v_cvt_pk_bf16_f32 v79, v88, v89
	global_store_dwordx4 v[80:81], v[76:79], off
	v_pk_mul_f32 v[74:75], v[74:75], v[82:83] op_sel_hi:[1,0]
	s_nop 0
	v_pk_mul_f32 v[76:77], v[70:71], v[82:83] op_sel_hi:[1,0]
	v_pk_mul_f32 v[70:71], v[68:69], v[82:83] op_sel_hi:[1,0]
	v_cvt_pk_bf16_f32 v68, v72, v73
	v_cvt_pk_bf16_f32 v69, v74, v75
	s_nop 0
	v_cvt_pk_bf16_f32 v70, v70, v71
	v_cvt_pk_bf16_f32 v71, v76, v77
	global_store_dwordx4 v[80:81], v[68:71], off offset:64
	s_nop 1
	v_add_u32_e32 v68, 0x80, v158
	v_mad_i64_i32 v[68:69], s[40:41], v68, s25, v[134:135]
	v_lshl_add_u64 v[68:69], v[68:69], 0, v[136:137]
	v_pk_mul_f32 v[70:71], v[62:63], v[138:139] op_sel_hi:[1,0]
	v_pk_mul_f32 v[62:63], v[60:61], v[138:139] op_sel_hi:[1,0]
	v_cvt_pk_bf16_f32 v60, v64, v65
	v_cvt_pk_bf16_f32 v61, v66, v67
	s_nop 0
	v_cvt_pk_bf16_f32 v62, v62, v63
	v_cvt_pk_bf16_f32 v63, v70, v71
	global_store_dwordx4 v[68:69], v[60:63], off
	s_nop 1
	v_pk_mul_f32 v[60:61], v[50:51], v[138:139] op_sel_hi:[1,0]
	v_pk_mul_f32 v[50:51], v[48:49], v[138:139] op_sel_hi:[1,0]
	v_cvt_pk_bf16_f32 v48, v56, v57
	v_cvt_pk_bf16_f32 v49, v58, v59
	s_nop 0
	v_cvt_pk_bf16_f32 v50, v50, v51
	v_cvt_pk_bf16_f32 v51, v60, v61
	global_store_dwordx4 v[68:69], v[48:51], off offset:64
	s_nop 1
	v_add_u32_e32 v48, 0x90, v158
	v_mad_i64_i32 v[48:49], s[40:41], v48, s25, v[134:135]
	v_mov_b32_e32 v50, v139
	v_lshl_add_u64 v[48:49], v[48:49], 0, v[136:137]
	v_pk_mul_f32 v[54:55], v[54:55], v[50:51] op_sel_hi:[1,0]
	v_pk_mul_f32 v[52:53], v[52:53], v[50:51] op_sel_hi:[1,0]
	v_pk_mul_f32 v[56:57], v[46:47], v[50:51] op_sel_hi:[1,0]
	v_pk_mul_f32 v[46:47], v[44:45], v[50:51] op_sel_hi:[1,0]
	v_cvt_pk_bf16_f32 v44, v52, v53
	v_cvt_pk_bf16_f32 v45, v54, v55
	v_pk_mul_f32 v[40:41], v[40:41], v[50:51] op_sel_hi:[1,0]
	v_cvt_pk_bf16_f32 v46, v46, v47
	v_cvt_pk_bf16_f32 v47, v56, v57
	global_store_dwordx4 v[48:49], v[44:47], off
	v_pk_mul_f32 v[42:43], v[42:43], v[50:51] op_sel_hi:[1,0]
	s_nop 0
	v_pk_mul_f32 v[44:45], v[34:35], v[50:51] op_sel_hi:[1,0]
	v_pk_mul_f32 v[34:35], v[32:33], v[50:51] op_sel_hi:[1,0]
	v_cvt_pk_bf16_f32 v32, v40, v41
	v_cvt_pk_bf16_f32 v33, v42, v43
	s_nop 0
	v_cvt_pk_bf16_f32 v34, v34, v35
	v_cvt_pk_bf16_f32 v35, v44, v45
	global_store_dwordx4 v[48:49], v[32:35], off offset:64
	s_nop 1
	v_add_u32_e32 v32, 0xa0, v158
	v_mad_i64_i32 v[32:33], s[40:41], v32, s25, v[134:135]
	v_lshl_add_u64 v[32:33], v[32:33], 0, v[136:137]
	v_pk_mul_f32 v[34:35], v[38:39], v[132:133] op_sel_hi:[1,0]
	v_pk_mul_f32 v[38:39], v[30:31], v[132:133] op_sel_hi:[1,0]
	v_pk_mul_f32 v[30:31], v[28:29], v[132:133] op_sel_hi:[1,0]
	v_cvt_pk_bf16_f32 v28, v36, v37
	v_cvt_pk_bf16_f32 v29, v34, v35
	s_nop 0
	v_cvt_pk_bf16_f32 v30, v30, v31
	v_cvt_pk_bf16_f32 v31, v38, v39
	global_store_dwordx4 v[32:33], v[28:31], off
	s_nop 1
	v_pk_mul_f32 v[28:29], v[18:19], v[132:133] op_sel_hi:[1,0]
	v_pk_mul_f32 v[18:19], v[16:17], v[132:133] op_sel_hi:[1,0]
	v_cvt_pk_bf16_f32 v16, v24, v25
	v_cvt_pk_bf16_f32 v17, v26, v27
	s_nop 0
	v_cvt_pk_bf16_f32 v18, v18, v19
	v_cvt_pk_bf16_f32 v19, v28, v29
	global_store_dwordx4 v[32:33], v[16:19], off offset:64
	s_nop 1
	v_add_u32_e32 v16, 0xb0, v158
	v_mad_i64_i32 v[16:17], s[40:41], v16, s25, v[134:135]
	v_mov_b32_e32 v18, v133
	v_lshl_add_u64 v[16:17], v[16:17], 0, v[136:137]
	v_pk_mul_f32 v[22:23], v[22:23], v[18:19] op_sel_hi:[1,0]
	v_pk_mul_f32 v[20:21], v[20:21], v[18:19] op_sel_hi:[1,0]
	v_pk_mul_f32 v[24:25], v[14:15], v[18:19] op_sel_hi:[1,0]
	v_pk_mul_f32 v[14:15], v[12:13], v[18:19] op_sel_hi:[1,0]
	v_cvt_pk_bf16_f32 v12, v20, v21
	v_cvt_pk_bf16_f32 v13, v22, v23
	v_pk_mul_f32 v[10:11], v[10:11], v[18:19] op_sel_hi:[1,0]
	v_cvt_pk_bf16_f32 v14, v14, v15
	v_cvt_pk_bf16_f32 v15, v24, v25
	global_store_dwordx4 v[16:17], v[12:15], off
	v_pk_mul_f32 v[8:9], v[8:9], v[18:19] op_sel_hi:[1,0]
	s_nop 0
	v_pk_mul_f32 v[12:13], v[6:7], v[18:19] op_sel_hi:[1,0]
	v_pk_mul_f32 v[6:7], v[4:5], v[18:19] op_sel_hi:[1,0]
	v_cvt_pk_bf16_f32 v4, v8, v9
	v_cvt_pk_bf16_f32 v5, v10, v11
	s_nop 0
	v_cvt_pk_bf16_f32 v6, v6, v7
	v_cvt_pk_bf16_f32 v7, v12, v13
	global_store_dwordx4 v[16:17], v[4:7], off offset:64
	s_and_b64 vcc, exec, s[6:7]
	s_mov_b64 s[6:7], -1
	s_cbranch_vccnz .LBB0_667
